# attn g>0: hoist LSE and prev-O loads above Q loads
# baseline (speedup 1.0000x reference)
; #define LAS __attribute__((address_space(3)))
; __device__ __forceinline__ void attn_phase(LAS unsigned char* lds, const bf16* Qg, const bf16* Kg, const bf16* Vg  , bf16* OB, float* LSE, int g, int dsh, int u_lo, int u_hi) {
;     ...
;         ATTN_DECODE(u, h, Q0, tokbase)
; #pragma unroll
;         for (int it = 0; it < 12; ++it) { const int piece = tid + 512 * it; const int kv = piece >= 3072 ? 1 : 0; const int pr = piece - 3072 * kv; const int row = pr >> 3, ch = pr & 7;
;             const bool live = (Q0 - 128 + row) >= 0; v4u val = kvr[it]; if (!live) val = (v4u){0u, 0u, 0u, 0u};
;             *(LAS v4u*)((kv ? Vl : Kl) + row * AT_PITCH + ch * 16) = val; }
.LBB0_141:
	s_waitcnt vmcnt(0)
	v_mov_b32_e32 v167, v166
	s_movk_i32 s23, 0xbff
	s_mov_b32 s36, s2
	s_ashr_i32 s2, s2, 4
	v_lshlrev_b32_e32 v0, 4, v167
	v_cmp_lt_i32_e64 s[40:41], s23, v167
	s_and_b32 s79, s2, s31
	v_and_b32_e32 v2, 0x70, v0
	v_cndmask_b32_e64 v0, 0, v196, s[40:41]
	s_lshl_b32 s78, s79, 8
	v_add_u32_e32 v0, v0, v167
	v_readlane_b32 s23, v250, 15
	s_sub_i32 s37, 0x7f, s78
	v_ashrrev_i32_e32 v3, 3, v0
	v_mov_b32_e32 v0, s23
	v_cmp_lt_i32_e32 vcc, s37, v3
	v_cndmask_b32_e64 v8, 0, v0, s[40:41]
	v_mul_lo_u32 v9, v3, s97
	s_movk_i32 s23, 0x9ff
	s_waitcnt vmcnt(11)
	v_cndmask_b32_e32 v7, 0, v85, vcc
	v_cndmask_b32_e32 v6, 0, v84, vcc
	v_cndmask_b32_e32 v5, 0, v83, vcc
	v_cndmask_b32_e32 v4, 0, v82, vcc
	v_add3_u32 v8, v8, v9, v2
	v_cmp_lt_i32_e32 vcc, s23, v167
	ds_write_b128 v8, v[4:7]
	s_movk_i32 s23, 0x7ff
	v_cndmask_b32_e32 v4, 0, v196, vcc
	v_add3_u32 v4, v167, v4, s64
	v_ashrrev_i32_e32 v8, 3, v4
	v_cmp_lt_i32_e64 s[38:39], s37, v8
	v_cndmask_b32_e32 v9, 0, v0, vcc
	v_mul_lo_u32 v10, v8, s97
	s_waitcnt vmcnt(10)
	v_cndmask_b32_e64 v7, 0, v89, s[38:39]
	v_cndmask_b32_e64 v6, 0, v88, s[38:39]
	v_cndmask_b32_e64 v5, 0, v87, s[38:39]
	v_cndmask_b32_e64 v4, 0, v86, s[38:39]
	v_add3_u32 v9, v9, v10, v2
	v_cmp_lt_i32_e64 s[38:39], s23, v167
	ds_write_b128 v9, v[4:7]
	s_movk_i32 s23, 0x400
	v_cndmask_b32_e64 v4, 0, v196, s[38:39]
	v_add3_u32 v4, v167, v4, s23
	v_ashrrev_i32_e32 v9, 3, v4
	v_cmp_lt_i32_e64 s[42:43], s37, v9
	v_cndmask_b32_e64 v10, 0, v0, s[38:39]
	v_mul_lo_u32 v11, v9, s97
	s_movk_i32 s23, 0x5ff
	s_waitcnt vmcnt(9)
	v_cndmask_b32_e64 v7, 0, v93, s[42:43]
	v_cndmask_b32_e64 v6, 0, v92, s[42:43]
	v_cndmask_b32_e64 v5, 0, v91, s[42:43]
	v_cndmask_b32_e64 v4, 0, v90, s[42:43]
	v_add3_u32 v10, v10, v11, v2
	v_cmp_lt_i32_e64 s[42:43], s23, v167
	ds_write_b128 v10, v[4:7]
	s_movk_i32 s23, 0x600
	v_cndmask_b32_e64 v4, 0, v196, s[42:43]
	v_add3_u32 v4, v167, v4, s23
	v_ashrrev_i32_e32 v10, 3, v4
	v_cmp_lt_i32_e64 s[44:45], s37, v10
	v_cndmask_b32_e64 v11, 0, v0, s[42:43]
	v_mul_lo_u32 v12, v10, s97
	s_movk_i32 s23, 0x3ff
	s_waitcnt vmcnt(8)
	v_cndmask_b32_e64 v7, 0, v97, s[44:45]
	v_cndmask_b32_e64 v6, 0, v96, s[44:45]
	v_cndmask_b32_e64 v5, 0, v95, s[44:45]
	v_cndmask_b32_e64 v4, 0, v94, s[44:45]
	v_add3_u32 v11, v11, v12, v2
	v_cmp_lt_i32_e64 s[44:45], s23, v167
	ds_write_b128 v11, v[4:7]
	s_movk_i32 s23, 0x800
	v_cndmask_b32_e64 v4, 0, v196, s[44:45]
	v_add3_u32 v4, v167, v4, s23
	v_ashrrev_i32_e32 v11, 3, v4
	v_cmp_lt_i32_e64 s[46:47], s37, v11
	v_cndmask_b32_e64 v12, 0, v0, s[44:45]
	v_mul_lo_u32 v13, v11, s97
	s_movk_i32 s23, 0x1ff
	s_waitcnt vmcnt(7)
	v_cndmask_b32_e64 v7, 0, v101, s[46:47]
	v_cndmask_b32_e64 v6, 0, v100, s[46:47]
	v_cndmask_b32_e64 v5, 0, v99, s[46:47]
	v_cndmask_b32_e64 v4, 0, v98, s[46:47]
	v_add3_u32 v12, v12, v13, v2
	v_cmp_lt_i32_e64 s[46:47], s23, v167
	ds_write_b128 v12, v[4:7]
	s_movk_i32 s23, 0xa00
	v_cndmask_b32_e64 v4, 0, v196, s[46:47]
	v_add3_u32 v4, v167, v4, s23
	v_ashrrev_i32_e32 v12, 3, v4
	v_cmp_lt_i32_e64 s[48:49], s37, v12
	v_cndmask_b32_e64 v13, 0, v0, s[46:47]
	v_mul_lo_u32 v14, v12, s97
	s_waitcnt vmcnt(6)
	v_cndmask_b32_e64 v7, 0, v105, s[48:49]
	v_cndmask_b32_e64 v6, 0, v104, s[48:49]
	v_cndmask_b32_e64 v5, 0, v103, s[48:49]
	v_cndmask_b32_e64 v4, 0, v102, s[48:49]
	v_add3_u32 v13, v13, v14, v2
	ds_write_b128 v13, v[4:7]
	v_add_u32_e32 v4, 0xc00, v167
	v_cmp_lt_i32_e64 s[48:49], -1, v167
	s_movk_i32 s23, 0xfdff
	s_ashr_i32 s20, s36, 8
	v_cndmask_b32_e64 v4, v4, v167, s[48:49]
	v_ashrrev_i32_e32 v13, 3, v4
	v_cmp_lt_i32_e64 s[50:51], s37, v13
	v_cndmask_b32_e64 v14, 0, v0, s[48:49]
	v_mul_lo_u32 v15, v13, s97
	s_waitcnt vmcnt(5)
	v_cndmask_b32_e64 v7, 0, v109, s[50:51]
	v_cndmask_b32_e64 v6, 0, v108, s[50:51]
	v_cndmask_b32_e64 v5, 0, v107, s[50:51]
	v_cndmask_b32_e64 v4, 0, v106, s[50:51]
	v_add3_u32 v14, v14, v15, v2
	v_cmp_lt_i32_e64 s[50:51], s23, v167
	ds_write_b128 v14, v[4:7]
	s_movk_i32 s23, 0xe00
	v_cndmask_b32_e64 v4, 0, v196, s[50:51]
	v_add3_u32 v4, v167, v4, s23
	v_ashrrev_i32_e32 v14, 3, v4
	v_cmp_lt_i32_e64 s[52:53], s37, v14
	v_cndmask_b32_e64 v15, 0, v0, s[50:51]
	v_mul_lo_u32 v16, v14, s97
	s_movk_i32 s23, 0xfbff
	s_waitcnt vmcnt(4)
	v_cndmask_b32_e64 v7, 0, v113, s[52:53]
	v_cndmask_b32_e64 v6, 0, v112, s[52:53]
	v_cndmask_b32_e64 v5, 0, v111, s[52:53]
	v_cndmask_b32_e64 v4, 0, v110, s[52:53]
	v_add3_u32 v15, v15, v16, v2
	v_cmp_lt_i32_e64 s[52:53], s23, v167
	ds_write_b128 v15, v[4:7]
	s_movk_i32 s23, 0xf9ff
	v_cndmask_b32_e64 v4, 0, v196, s[52:53]
	v_add3_u32 v4, v167, v4, s72
	v_ashrrev_i32_e32 v15, 3, v4
	v_cmp_lt_i32_e64 s[54:55], s37, v15
	v_cndmask_b32_e64 v16, 0, v0, s[52:53]
	v_mul_lo_u32 v17, v15, s97
	s_waitcnt vmcnt(3)
	v_cndmask_b32_e64 v7, 0, v117, s[54:55]
	v_cndmask_b32_e64 v6, 0, v116, s[54:55]
	v_cndmask_b32_e64 v5, 0, v115, s[54:55]
	v_cndmask_b32_e64 v4, 0, v114, s[54:55]
	v_add3_u32 v16, v16, v17, v2
	v_cmp_lt_i32_e64 s[54:55], s23, v167
	ds_write_b128 v16, v[4:7]
	s_movk_i32 s23, 0x1200
	v_cndmask_b32_e64 v4, 0, v196, s[54:55]
	v_add3_u32 v4, v167, v4, s23
	v_ashrrev_i32_e32 v16, 3, v4
	v_cmp_lt_i32_e64 s[56:57], s37, v16
	v_cndmask_b32_e64 v17, 0, v0, s[54:55]
	v_mul_lo_u32 v18, v16, s97
	s_movk_i32 s23, 0xf7ff
	s_waitcnt vmcnt(2)
	v_cndmask_b32_e64 v7, 0, v121, s[56:57]
	v_cndmask_b32_e64 v6, 0, v120, s[56:57]
	v_cndmask_b32_e64 v5, 0, v119, s[56:57]
	v_cndmask_b32_e64 v4, 0, v118, s[56:57]
	v_add3_u32 v17, v17, v18, v2
	v_cmp_lt_i32_e64 s[56:57], s23, v167
	ds_write_b128 v17, v[4:7]
	s_movk_i32 s23, 0x1400
	v_cndmask_b32_e64 v4, 0, v196, s[56:57]
	v_add3_u32 v4, v167, v4, s23
	v_ashrrev_i32_e32 v17, 3, v4
	v_cmp_lt_i32_e64 s[58:59], s37, v17
	v_cndmask_b32_e64 v18, 0, v0, s[56:57]
	v_mul_lo_u32 v19, v17, s97
	s_movk_i32 s23, 0xf5ff
	s_waitcnt vmcnt(1)
; #define GAS __attribute__((address_space(1)))
; #define LAS __attribute__((address_space(3)))
; __device__ __forceinline__ unsigned cvtpk(float lo, float hi) { unsigned r; asm volatile("v_cvt_pk_bf16_f32 %0, %1, %2" : "=v"(r) : "v"(lo), "v"(hi)); return r; }
; __device__ __forceinline__ void attn_phase(LAS unsigned char* lds, const bf16* Qg, const bf16* Kg, const bf16* Vg  , bf16* OB, float* LSE, int g, int dsh, int u_lo, int u_hi) {
;     ...
;             *(LAS v4u*)((kv ? Vl : Kl) + row * AT_PITCH + ch * 16) = val; }
;         const int qpos = Q0 + 32 * wave + r; const size_t qtok = tokbase + (size_t)qpos * dil;
;     ...
;         if (g > 0) { const float lp = ((const GAS float*)LSE)[qtok * 16 + h]; const float mm = fmaxf(lp, lse); ea = __expf(lp - mm); eb = __expf(lse - mm); const float den = 1.0f / (ea + eb); lse = mm + __logf(ea + eb); ea *= den; eb *= den; }
;         eb *= inv;
;         LAS unsigned char* Ost = lds + 2 * AT_ROWS * AT_PITCH + wave * (32 * 136);
; #pragma unroll
;         for (int dt = 0; dt < 2; ++dt)
; #pragma unroll
;             for (int i4 = 0; i4 < 4; ++i4) { v2u w; w.x = cvtpk(o[dt][4 * i4] * eb, o[dt][4 * i4 + 1] * eb); w.y = cvtpk(o[dt][4 * i4 + 2] * eb, o[dt][4 * i4 + 3] * eb);
;                 *(LAS v2u*)(Ost + r * 136 + (32 * dt + 8 * i4 + 4 * hh) * 2) = w; }
;         asm volatile("s_waitcnt lgkmcnt(0)" ::: "memory");
;         const int rr0 = lane >> 3, cc = lane & 7;
;         v4u pv4[4];
;         if (g > 0) {
; #pragma unroll
;             for (int j4 = 0; j4 < 4; ++j4) pv4[j4] = *(const GAS v4u*)(OB + (tokbase + (size_t)(Q0 + 32 * wave + rr0 + 8 * j4) * dil) * 1024 + h * 64 + cc * 8); }
	v_cndmask_b32_e64 v7, 0, v125, s[58:59]
	v_cndmask_b32_e64 v6, 0, v124, s[58:59]
	v_cndmask_b32_e64 v5, 0, v123, s[58:59]
	v_cndmask_b32_e64 v4, 0, v122, s[58:59]
	v_add3_u32 v18, v18, v19, v2
	v_cmp_lt_i32_e64 s[58:59], s23, v167
	ds_write_b128 v18, v[4:7]
	s_movk_i32 s23, 0x1600
	v_cndmask_b32_e64 v4, 0, v196, s[58:59]
	v_add3_u32 v4, v167, v4, s23
	s_ashr_i32 s2, s2, s22
	v_readlane_b32 s80, v250, 59
	s_ashr_i32 s21, s20, 31
	v_ashrrev_i32_e32 v18, 3, v4
	s_and_b32 s2, s2, s80
	v_cmp_lt_i32_e64 s[62:63], s37, v18
	s_and_b32 s77, s36, 15
	s_lshl_b64 s[20:21], s[20:21], 12
	s_waitcnt vmcnt(0)
	v_cndmask_b32_e64 v7, 0, v129, s[62:63]
	v_cndmask_b32_e64 v6, 0, v128, s[62:63]
	v_cndmask_b32_e64 v5, 0, v127, s[62:63]
	v_cndmask_b32_e64 v4, 0, v126, s[62:63]
	v_cndmask_b32_e64 v0, 0, v0, s[58:59]
	v_mul_lo_u32 v19, v18, s97
	s_add_u32 s62, s20, s2
	v_add3_u32 v0, v0, v19, v2
	v_and_b32_e32 v169, 31, v167
	s_addc_u32 s63, s21, 0
	s_add_i32 s78, s78, s14
	ds_write_b128 v0, v[4:7]
	v_or_b32_e32 v4, s78, v169
	v_ashrrev_i32_e32 v5, 31, v4
	v_lshlrev_b64 v[4:5], s30, v[4:5]
	v_lshl_add_u64 v[164:165], v[4:5], 0, s[62:63]
	s_lshl_b32 s94, s77, 7
	s_add_i32 s2, s36, s66
	v_lshlrev_b64 v[4:5], 11, v[164:165]
	s_cmpk_gt_i32 s2, 0x7ff
	v_lshl_add_u64 v[4:5], s[68:69], 0, v[4:5]
	s_cselect_b64 s[20:21], -1, 0
	s_cmpk_lt_i32 s2, 0x800
	v_lshl_add_u64 v[4:5], v[4:5], 0, s[94:95]
	s_cselect_b32 s94, s2, s36
	s_ashr_i32 s36, s94, 4
	s_and_b32 s37, s36, s31
	s_ashr_i32 s36, s36, s22
	s_and_b32 s80, s36, s80
	s_ashr_i32 s36, s94, 8
	s_lshl_b32 s23, s37, 8
	s_ashr_i32 s37, s36, 31
	s_lshl_b64 s[36:37], s[36:37], 12
	v_bfe_u32 v168, v167, 5, 1
	s_add_u32 s36, s36, s80
	v_lshlrev_b32_e32 v0, 4, v168
	s_addc_u32 s37, s37, 0
	s_addk_i32 s23, 0xff80
	v_lshl_add_u64 v[4:5], v[4:5], 0, v[0:1]
	v_add_u32_e32 v3, s23, v3
	s_cmp_eq_u64 s[28:29], 0
	s_cbranch_scc1 .Lmy_attn_nopre
	v_lshlrev_b64 v[252:253], 6, v[164:165]
	v_lshl_add_u64 v[252:253], s[86:87], 0, v[252:253]
	s_lshl_b32 s100, s77, 2
	s_mov_b32 s101, 0
	v_lshl_add_u64 v[252:253], v[252:253], 0, s[100:101]
	global_load_dword v254, v[252:253], off
	s_lshl_b32 s100, s77, 7
	s_add_u32 s100, s18, s100
	s_addc_u32 s101, s19, 0
	v_and_b32_e32 v232, 63, v167
	v_and_b32_e32 v234, 7, v167
	v_lshrrev_b32_e32 v232, 3, v232
	v_lshlrev_b32_e32 v234, 4, v234
	v_mov_b32_e32 v235, 0
	v_or_b32_e32 v232, s78, v232
	v_mov_b32_e32 v233, 0
	v_lshl_add_u64 v[234:235], s[100:101], 0, v[234:235]
	v_lshlrev_b64 v[252:253], s30, v[232:233]
	v_lshl_add_u64 v[252:253], v[252:253], 0, s[62:63]
	v_lshlrev_b64 v[252:253], 11, v[252:253]
	v_lshl_add_u64 v[252:253], v[234:235], 0, v[252:253]
	global_load_dwordx4 v[216:219], v[252:253], off
	v_or_b32_e32 v232, 8, v232
	v_lshlrev_b64 v[252:253], s30, v[232:233]
	v_lshl_add_u64 v[252:253], v[252:253], 0, s[62:63]
	v_lshlrev_b64 v[252:253], 11, v[252:253]
	v_lshl_add_u64 v[252:253], v[234:235], 0, v[252:253]
	global_load_dwordx4 v[220:223], v[252:253], off
	v_xor_b32_e32 v232, 24, v232
	v_lshlrev_b64 v[252:253], s30, v[232:233]
	v_lshl_add_u64 v[252:253], v[252:253], 0, s[62:63]
	v_lshlrev_b64 v[252:253], 11, v[252:253]
	v_lshl_add_u64 v[252:253], v[234:235], 0, v[252:253]
	global_load_dwordx4 v[224:227], v[252:253], off
	v_or_b32_e32 v232, 8, v232
	v_lshlrev_b64 v[252:253], s30, v[232:233]
	v_lshl_add_u64 v[252:253], v[252:253], 0, s[62:63]
	v_lshlrev_b64 v[252:253], 11, v[252:253]
	v_lshl_add_u64 v[252:253], v[234:235], 0, v[252:253]
	global_load_dwordx4 v[228:231], v[252:253], off
; #define GAS __attribute__((address_space(1)))
; #define LAS __attribute__((address_space(3)))
; #define LDS_BAR() do { asm volatile("s_waitcnt lgkmcnt(0)" ::: "memory"); __builtin_amdgcn_s_barrier(); asm volatile("" ::: "memory"); } while (0)
; #define MFMA32(a, b, c) __builtin_amdgcn_mfma_f32_32x32x16_bf16((a), (b), (c), 0, 0, 0)
; __device__ __forceinline__ void attn_phase(LAS unsigned char* lds, const bf16* Qg, const bf16* Kg, const bf16* Vg  , bf16* OB, float* LSE, int g, int dsh, int u_lo, int u_hi) {
;     ...
;         for (int ks = 0; ks < 4; ++ks) qf[ks] = *(const GAS bf16x8*)(Qg + qtok * 1024 + h * 64 + 16 * ks + 8 * hh);
;         LDS_BAR();
;         { const int un0 = u + (int)gridDim.x; const int un = un0 < u_hi ? un0 : u;
;             ATTN_DECODE(un, hn, Q0n, tbn) ATTN_FETCH(hn, Q0n, tbn); }
;         f32x16 st[5];
;         const bool first = (Q0 == 0);
; #pragma unroll
;         for (int c = 0; c < 5; ++c) {
; #pragma unroll
;             for (int i = 0; i < 16; ++i) st[c][i] = 0.f;
;             if (!(first && (wave + c < 4)))
; #pragma unroll
;             for (int ks = 0; ks < 4; ++ks) { const bf16x8 kf = *(const LAS bf16x8*)(Kl + (32 * (wave + c) + r) * AT_PITCH + (16 * ks + 8 * hh) * 2); st[c] = MFMA32(kf, qf[ks], st[c]); } }
.Lmy_attn_nopre:
	global_load_dwordx4 v[158:161], v[4:5], off
	global_load_dwordx4 v[154:157], v[4:5], off offset:32
	global_load_dwordx4 v[150:153], v[4:5], off offset:64
	global_load_dwordx4 v[146:149], v[4:5], off offset:96
	v_max_i32_e32 v4, 0, v3
	v_mov_b32_e32 v5, v1
	v_lshlrev_b64 v[4:5], s30, v[4:5]
	v_mov_b32_e32 v19, s8
	v_mov_b32_e32 v20, s11
	v_mov_b32_e32 v21, s9
	v_mov_b32_e32 v22, s10
	v_lshl_add_u64 v[4:5], v[4:5], 0, s[36:37]
	v_cndmask_b32_e64 v7, v19, v20, s[40:41]
	v_cndmask_b32_e64 v6, v21, v22, s[40:41]
	v_lshlrev_b64 v[4:5], 11, v[4:5]
	s_lshl_b32 s40, s94, 7
	v_lshl_add_u64 v[4:5], v[6:7], 0, v[4:5]
	s_and_b32 s94, s40, 0x780
	v_lshl_add_u64 v[4:5], v[4:5], 0, s[94:95]
	v_mov_b32_e32 v3, v1
	s_waitcnt lgkmcnt(0)
	s_barrier
	v_lshl_add_u64 v[4:5], v[4:5], 0, v[2:3]
	global_load_dwordx4 v[82:85], v[4:5], off
	v_add_u32_e32 v4, s23, v8
	v_max_i32_e32 v4, 0, v4
	v_mov_b32_e32 v5, v1
	v_lshlrev_b64 v[4:5], s30, v[4:5]
	v_lshl_add_u64 v[4:5], v[4:5], 0, s[36:37]
	v_cndmask_b32_e32 v7, v19, v20, vcc
	v_cndmask_b32_e32 v6, v21, v22, vcc
	v_lshlrev_b64 v[4:5], 11, v[4:5]
	v_lshl_add_u64 v[4:5], v[6:7], 0, v[4:5]
	v_lshl_add_u64 v[4:5], v[4:5], 0, s[94:95]
	v_lshl_add_u64 v[4:5], v[4:5], 0, v[2:3]
	global_load_dwordx4 v[86:89], v[4:5], off
	v_add_u32_e32 v4, s23, v9
	v_max_i32_e32 v4, 0, v4
	v_mov_b32_e32 v5, v1
	v_lshlrev_b64 v[4:5], s30, v[4:5]
	v_lshl_add_u64 v[4:5], v[4:5], 0, s[36:37]
	v_cndmask_b32_e64 v7, v19, v20, s[38:39]
	v_cndmask_b32_e64 v6, v21, v22, s[38:39]
	v_lshlrev_b64 v[4:5], 11, v[4:5]
	v_lshl_add_u64 v[4:5], v[6:7], 0, v[4:5]
	v_lshl_add_u64 v[4:5], v[4:5], 0, s[94:95]
	v_lshl_add_u64 v[4:5], v[4:5], 0, v[2:3]
	global_load_dwordx4 v[90:93], v[4:5], off
	v_add_u32_e32 v4, s23, v10
	v_max_i32_e32 v4, 0, v4
	v_mov_b32_e32 v5, v1
	v_lshlrev_b64 v[4:5], s30, v[4:5]
	v_lshl_add_u64 v[4:5], v[4:5], 0, s[36:37]
	v_cndmask_b32_e64 v7, v19, v20, s[42:43]
	v_cndmask_b32_e64 v6, v21, v22, s[42:43]
	v_lshlrev_b64 v[4:5], 11, v[4:5]
	v_lshl_add_u64 v[4:5], v[6:7], 0, v[4:5]
	v_lshl_add_u64 v[4:5], v[4:5], 0, s[94:95]
	v_lshl_add_u64 v[4:5], v[4:5], 0, v[2:3]
	global_load_dwordx4 v[94:97], v[4:5], off
	v_add_u32_e32 v4, s23, v11
	v_max_i32_e32 v4, 0, v4
	v_mov_b32_e32 v5, v1
	v_lshlrev_b64 v[4:5], s30, v[4:5]
	v_lshl_add_u64 v[4:5], v[4:5], 0, s[36:37]
	v_cndmask_b32_e64 v7, v19, v20, s[44:45]
	v_cndmask_b32_e64 v6, v21, v22, s[44:45]
	v_lshlrev_b64 v[4:5], 11, v[4:5]
	v_lshl_add_u64 v[4:5], v[6:7], 0, v[4:5]
	v_lshl_add_u64 v[4:5], v[4:5], 0, s[94:95]
	v_lshl_add_u64 v[4:5], v[4:5], 0, v[2:3]
	global_load_dwordx4 v[98:101], v[4:5], off
	v_add_u32_e32 v4, s23, v12
	v_max_i32_e32 v4, 0, v4
	v_mov_b32_e32 v5, v1
	v_lshlrev_b64 v[4:5], s30, v[4:5]
	v_lshl_add_u64 v[4:5], v[4:5], 0, s[36:37]
	v_cndmask_b32_e64 v7, v19, v20, s[46:47]
	v_cndmask_b32_e64 v6, v21, v22, s[46:47]
	v_lshlrev_b64 v[4:5], 11, v[4:5]
	v_lshl_add_u64 v[4:5], v[6:7], 0, v[4:5]
	v_lshl_add_u64 v[4:5], v[4:5], 0, s[94:95]
	v_lshl_add_u64 v[4:5], v[4:5], 0, v[2:3]
	global_load_dwordx4 v[102:105], v[4:5], off
	v_add_u32_e32 v4, s23, v13
	v_max_i32_e32 v4, 0, v4
	v_mov_b32_e32 v5, v1
	v_lshlrev_b64 v[4:5], s30, v[4:5]
	v_lshl_add_u64 v[4:5], v[4:5], 0, s[36:37]
	v_cndmask_b32_e64 v7, v19, v20, s[48:49]
	v_cndmask_b32_e64 v6, v21, v22, s[48:49]
	v_lshlrev_b64 v[4:5], 11, v[4:5]
	v_lshl_add_u64 v[4:5], v[6:7], 0, v[4:5]
	v_lshl_add_u64 v[4:5], v[4:5], 0, s[94:95]
	v_lshl_add_u64 v[4:5], v[4:5], 0, v[2:3]
	global_load_dwordx4 v[106:109], v[4:5], off
	v_add_u32_e32 v4, s23, v14
	v_max_i32_e32 v4, 0, v4
	v_mov_b32_e32 v5, v1
	v_lshlrev_b64 v[4:5], s30, v[4:5]
	v_lshl_add_u64 v[4:5], v[4:5], 0, s[36:37]
	v_cndmask_b32_e64 v7, v19, v20, s[50:51]
	v_cndmask_b32_e64 v6, v21, v22, s[50:51]
	v_lshlrev_b64 v[4:5], 11, v[4:5]
	v_lshl_add_u64 v[4:5], v[6:7], 0, v[4:5]
	v_lshl_add_u64 v[4:5], v[4:5], 0, s[94:95]
	v_lshl_add_u64 v[4:5], v[4:5], 0, v[2:3]
	global_load_dwordx4 v[110:113], v[4:5], off
	v_add_u32_e32 v4, s23, v15
	v_max_i32_e32 v4, 0, v4
	v_mov_b32_e32 v5, v1
	v_lshlrev_b64 v[4:5], s30, v[4:5]
	v_lshl_add_u64 v[4:5], v[4:5], 0, s[36:37]
	v_cndmask_b32_e64 v7, v19, v20, s[52:53]
	v_cndmask_b32_e64 v6, v21, v22, s[52:53]
	v_lshlrev_b64 v[4:5], 11, v[4:5]
	v_lshl_add_u64 v[4:5], v[6:7], 0, v[4:5]
	v_lshl_add_u64 v[4:5], v[4:5], 0, s[94:95]
	v_lshl_add_u64 v[4:5], v[4:5], 0, v[2:3]
	global_load_dwordx4 v[114:117], v[4:5], off
	v_add_u32_e32 v4, s23, v16
	v_max_i32_e32 v4, 0, v4
	v_mov_b32_e32 v5, v1
	v_lshlrev_b64 v[4:5], s30, v[4:5]
	v_lshl_add_u64 v[4:5], v[4:5], 0, s[36:37]
	v_cndmask_b32_e64 v7, v19, v20, s[54:55]
	v_cndmask_b32_e64 v6, v21, v22, s[54:55]
	v_lshlrev_b64 v[4:5], 11, v[4:5]
	v_lshl_add_u64 v[4:5], v[6:7], 0, v[4:5]
	v_lshl_add_u64 v[4:5], v[4:5], 0, s[94:95]
	v_lshl_add_u64 v[4:5], v[4:5], 0, v[2:3]
	global_load_dwordx4 v[118:121], v[4:5], off
	v_add_u32_e32 v4, s23, v17
	v_max_i32_e32 v4, 0, v4
	v_mov_b32_e32 v5, v1
	v_lshlrev_b64 v[4:5], s30, v[4:5]
	v_lshl_add_u64 v[4:5], v[4:5], 0, s[36:37]
	v_cndmask_b32_e64 v7, v19, v20, s[56:57]
	v_cndmask_b32_e64 v6, v21, v22, s[56:57]
	v_lshlrev_b64 v[4:5], 11, v[4:5]
	v_lshl_add_u64 v[4:5], v[6:7], 0, v[4:5]
	v_lshl_add_u64 v[4:5], v[4:5], 0, s[94:95]
	v_lshl_add_u64 v[4:5], v[4:5], 0, v[2:3]
	global_load_dwordx4 v[122:125], v[4:5], off
	v_add_u32_e32 v4, s23, v18
	v_max_i32_e32 v4, 0, v4
	v_mov_b32_e32 v5, v1
	v_lshlrev_b64 v[4:5], s30, v[4:5]
	v_lshl_add_u64 v[4:5], v[4:5], 0, s[36:37]
	v_cndmask_b32_e64 v7, v19, v20, s[58:59]
	v_cndmask_b32_e64 v6, v21, v22, s[58:59]
	v_lshlrev_b64 v[4:5], 11, v[4:5]
	v_lshl_add_u64 v[4:5], v[6:7], 0, v[4:5]
	v_lshl_add_u64 v[4:5], v[4:5], 0, s[94:95]
	v_lshl_add_u64 v[2:3], v[4:5], 0, v[2:3]
	global_load_dwordx4 v[126:129], v[2:3], off
	s_cmp_lg_u32 s79, 0
	s_cselect_b64 s[38:39], -1, 0
	s_or_b64 s[54:55], s[38:39], s[90:91]
	v_cndmask_b32_e64 v3, 0, 1, s[54:55]
	v_add_u32_e32 v0, 0, v0
	v_mov_b32_e32 v2, 0
	v_cmp_ne_u32_e64 s[46:47], 1, v3
	s_andn2_b64 vcc, exec, s[54:55]
	v_mov_b32_e32 v18, 0
	v_mov_b32_e32 v19, 0
	v_mov_b32_e32 v20, 0
	v_mov_b32_e32 v21, 0
	v_mov_b32_e32 v22, 0
	v_mov_b32_e32 v23, 0
	v_mov_b32_e32 v24, 0
	v_mov_b32_e32 v25, 0
	v_mov_b32_e32 v26, 0
	v_mov_b32_e32 v27, 0
	v_mov_b32_e32 v28, 0
	v_mov_b32_e32 v29, 0
	v_mov_b32_e32 v30, 0
	v_mov_b32_e32 v31, 0
	v_mov_b32_e32 v32, 0
	v_mov_b32_e32 v33, 0
	s_cbranch_vccnz .LBB0_143
	v_or_b32_e32 v3, s14, v169
	v_mad_u64_u32 v[8:9], s[36:37], v3, s97, v[0:1]
	ds_read_b128 v[4:7], v8
	s_waitcnt vmcnt(15) lgkmcnt(0)
	v_mfma_f32_32x32x16_bf16 v[18:33], v[4:7], v[158:161], 0
	ds_read_b128 v[4:7], v8 offset:32
	s_waitcnt vmcnt(14) lgkmcnt(0)
	v_mfma_f32_32x32x16_bf16 v[18:33], v[4:7], v[154:157], v[18:33]
	ds_read_b128 v[4:7], v8 offset:64
	s_waitcnt vmcnt(13) lgkmcnt(0)
	v_mfma_f32_32x32x16_bf16 v[18:33], v[4:7], v[150:153], v[18:33]
	ds_read_b128 v[4:7], v8 offset:96
	s_waitcnt vmcnt(12) lgkmcnt(0)
	v_mfma_f32_32x32x16_bf16 v[18:33], v[4:7], v[146:149], v[18:33]

; #define GAS __attribute__((address_space(1)))
; __device__ __forceinline__ void attn_phase(LAS unsigned char* lds, const bf16* Qg, const bf16* Kg, const bf16* Vg  , bf16* OB, float* LSE, int g, int dsh, int u_lo, int u_hi) {
;     ...
;         const float inv = 1.0f / l; float lse = mx * 0.125f + __logf(l);
;         float ea = 0.f, eb = 1.f;
;         if (g > 0) { const float lp = ((const GAS float*)LSE)[qtok * 16 + h]; const float mm = fmaxf(lp, lse); ea = __expf(lp - mm); eb = __expf(lse - mm); const float den = 1.0f / (ea + eb); lse = mm + __logf(ea + eb); ea *= den; eb *= den; }
.LBB0_159:
	s_waitcnt lgkmcnt(0)
	v_add_f32_e32 v0, v50, v51
	v_cmp_gt_f32_e32 vcc, s23, v0
	v_mov_b32_e32 v52, 0
	s_nop 0
	v_cndmask_b32_e64 v2, 0, 32, vcc
	v_ldexp_f32 v2, v0, v2
	v_log_f32_e32 v2, v2
	v_cndmask_b32_e32 v3, 0, v198, vcc
	v_mul_f32_e32 v4, 0x3f317217, v2
	v_fma_f32 v4, v2, s58, -v4
	v_fmac_f32_e32 v4, 0x3377d1cf, v2
	v_fmac_f32_e32 v4, 0x3f317217, v2
	v_cmp_lt_f32_e64 vcc, |v2|, s59
	s_nop 1
	v_cndmask_b32_e32 v2, v2, v4, vcc
	v_sub_f32_e32 v50, v2, v3
	v_lshlrev_b64 v[2:3], 6, v[164:165]
	v_fmac_f32_e32 v50, 0x3e000000, v49
	s_andn2_b64 vcc, exec, s[28:29]
	v_lshl_add_u64 v[48:49], s[86:87], 0, v[2:3]
	s_cbranch_vccnz .LBB0_163
	s_waitcnt vmcnt(12)
	v_mov_b32_e32 v2, v254
	v_max_f32_e32 v4, v50, v50
	v_max_f32_e32 v3, v2, v2
	v_max_f32_e32 v3, v3, v4
	v_sub_f32_e32 v2, v2, v3
	v_sub_f32_e32 v4, v50, v3
	v_mul_f32_e32 v2, 0x3fb8aa3b, v2
	v_mul_f32_e32 v4, 0x3fb8aa3b, v4
	v_exp_f32_e32 v2, v2
	v_exp_f32_e32 v4, v4
	s_nop 0
	v_add_f32_e32 v5, v2, v4
	v_div_scale_f32 v6, s[36:37], v5, v5, 1.0
	v_rcp_f32_e32 v7, v6
	s_nop 0
	v_fma_f32 v8, -v6, v7, 1.0
	v_fmac_f32_e32 v7, v8, v7
	v_div_scale_f32 v8, vcc, 1.0, v5, 1.0
	v_mul_f32_e32 v9, v8, v7
	v_fma_f32 v10, -v6, v9, v8
	v_fmac_f32_e32 v9, v10, v7
	v_fma_f32 v6, -v6, v9, v8
	v_div_fmas_f32 v6, v6, v7, v9
	v_cmp_gt_f32_e32 vcc, s23, v5
	v_div_fixup_f32 v6, v6, v5, 1.0
	v_mul_f32_e32 v52, v2, v6
	v_cndmask_b32_e64 v7, 0, 32, vcc
	v_ldexp_f32 v5, v5, v7
	v_log_f32_e32 v5, v5
	v_mul_f32_e32 v2, v4, v6
	v_mul_f32_e32 v7, 0x3f317217, v5
	v_fma_f32 v7, v5, s58, -v7
	v_fmac_f32_e32 v7, 0x3377d1cf, v5
	v_fmac_f32_e32 v7, 0x3f317217, v5
	v_cmp_lt_f32_e64 s[38:39], |v5|, s59
	s_nop 1
	v_cndmask_b32_e64 v5, v5, v7, s[38:39]
	v_cndmask_b32_e32 v7, 0, v198, vcc
	v_sub_f32_e32 v5, v5, v7
	v_add_f32_e32 v50, v3, v5
	s_branch .LBB0_164

; #define GAS __attribute__((address_space(1)))
; #define LAS __attribute__((address_space(3)))
; __device__ __forceinline__ unsigned cvtpk(float lo, float hi) { unsigned r; asm volatile("v_cvt_pk_bf16_f32 %0, %1, %2" : "=v"(r) : "v"(lo), "v"(hi)); return r; }
; __device__ __forceinline__ void attn_phase(LAS unsigned char* lds, const bf16* Qg, const bf16* Kg, const bf16* Vg  , bf16* OB, float* LSE, int g, int dsh, int u_lo, int u_hi) {
;     ...
;         eb *= inv;
;         LAS unsigned char* Ost = lds + 2 * AT_ROWS * AT_PITCH + wave * (32 * 136);
; #pragma unroll
;         for (int dt = 0; dt < 2; ++dt)
; #pragma unroll
;             for (int i4 = 0; i4 < 4; ++i4) { v2u w; w.x = cvtpk(o[dt][4 * i4] * eb, o[dt][4 * i4 + 1] * eb); w.y = cvtpk(o[dt][4 * i4 + 2] * eb, o[dt][4 * i4 + 3] * eb);
;                 *(LAS v2u*)(Ost + r * 136 + (32 * dt + 8 * i4 + 4 * hh) * 2) = w; }
;         asm volatile("s_waitcnt lgkmcnt(0)" ::: "memory");
;         const int rr0 = lane >> 3, cc = lane & 7;
;         v4u pv4[4];
;         if (g > 0) {
; #pragma unroll
;             for (int j4 = 0; j4 < 4; ++j4) pv4[j4] = *(const GAS v4u*)(OB + (tokbase + (size_t)(Q0 + 32 * wave + rr0 + 8 * j4) * dil) * 1024 + h * 64 + cc * 8); }
.LBB0_164:
	v_div_scale_f32 v3, s[36:37], v0, v0, 1.0
	v_rcp_f32_e32 v4, v3
	v_lshlrev_b32_e32 v5, 3, v168
	v_and_b32_e32 v51, 63, v167
	s_lshl_b32 s38, s77, 6
	v_fma_f32 v6, -v3, v4, 1.0
	v_fmac_f32_e32 v4, v6, v4
	v_div_scale_f32 v6, vcc, 1.0, v0, 1.0
	v_mul_f32_e32 v7, v6, v4
	v_fma_f32 v8, -v3, v7, v6
	v_fmac_f32_e32 v7, v8, v4
	v_fma_f32 v3, -v3, v7, v6
	v_div_fmas_f32 v3, v3, v4, v7
	v_div_fixup_f32 v0, v3, v0, 1.0
	v_mul_f32_e32 v0, v0, v2
	v_mul_u32_u24_e32 v2, 0x88, v169
	v_add3_u32 v4, s15, v2, v5
	v_mul_f32_e32 v2, v32, v0
	v_mul_f32_e32 v3, v33, v0
	v_cvt_pk_bf16_f32 v2, v2, v3
	v_mul_f32_e32 v3, v34, v0
	v_mul_f32_e32 v5, v35, v0
	v_cvt_pk_bf16_f32 v3, v3, v5
	ds_write_b64 v4, v[2:3]
	v_mul_f32_e32 v2, v36, v0
	v_mul_f32_e32 v3, v37, v0
	v_cvt_pk_bf16_f32 v2, v2, v3
	v_mul_f32_e32 v3, v38, v0
	v_mul_f32_e32 v5, v39, v0
	v_cvt_pk_bf16_f32 v3, v3, v5
	ds_write_b64 v4, v[2:3] offset:16
	v_mul_f32_e32 v2, v40, v0
	v_mul_f32_e32 v3, v41, v0
	v_cvt_pk_bf16_f32 v2, v2, v3
	v_mul_f32_e32 v3, v42, v0
	v_mul_f32_e32 v5, v43, v0
	v_cvt_pk_bf16_f32 v3, v3, v5
	ds_write_b64 v4, v[2:3] offset:32
	v_mul_f32_e32 v2, v44, v0
	v_mul_f32_e32 v3, v45, v0
	v_cvt_pk_bf16_f32 v2, v2, v3
	v_mul_f32_e32 v3, v46, v0
	v_mul_f32_e32 v5, v47, v0
	v_cvt_pk_bf16_f32 v3, v3, v5
	ds_write_b64 v4, v[2:3] offset:48
	v_mul_f32_e32 v2, v16, v0
	v_mul_f32_e32 v3, v17, v0
	v_cvt_pk_bf16_f32 v2, v2, v3
	v_mul_f32_e32 v3, v18, v0
	v_mul_f32_e32 v5, v19, v0
	v_cvt_pk_bf16_f32 v3, v3, v5
	ds_write_b64 v4, v[2:3] offset:64
	v_mul_f32_e32 v2, v20, v0
	v_mul_f32_e32 v3, v21, v0
	v_cvt_pk_bf16_f32 v2, v2, v3
	v_mul_f32_e32 v3, v22, v0
	v_mul_f32_e32 v5, v23, v0
	v_cvt_pk_bf16_f32 v3, v3, v5
	ds_write_b64 v4, v[2:3] offset:80
	v_mul_f32_e32 v2, v24, v0
	v_mul_f32_e32 v3, v25, v0
	v_cvt_pk_bf16_f32 v2, v2, v3
	v_mul_f32_e32 v3, v26, v0
	v_mul_f32_e32 v5, v27, v0
	v_cvt_pk_bf16_f32 v3, v3, v5
	ds_write_b64 v4, v[2:3] offset:96
	v_mul_f32_e32 v2, v28, v0
	v_mul_f32_e32 v3, v29, v0
	v_cvt_pk_bf16_f32 v2, v2, v3
	v_mul_f32_e32 v3, v30, v0
	v_mul_f32_e32 v0, v31, v0
	v_cvt_pk_bf16_f32 v3, v3, v0
	ds_write_b64 v4, v[2:3] offset:112
	s_waitcnt lgkmcnt(0)
	v_lshrrev_b32_e32 v30, 3, v51
	v_and_b32_e32 v18, 7, v167
	v_or_b32_e32 v28, s78, v30
	s_and_b64 vcc, exec, s[28:29]
	v_lshlrev_b32_e32 v0, 3, v18
	v_ashrrev_i32_e32 v29, 31, v28
	s_cbranch_vccz .LBB0_181
	v_mov_b64_e32 v[2:3], v[216:217]
	v_mov_b64_e32 v[4:5], v[218:219]
	v_mov_b64_e32 v[6:7], v[220:221]
	v_mov_b64_e32 v[8:9], v[222:223]
	v_mov_b64_e32 v[10:11], v[224:225]
	v_mov_b64_e32 v[12:13], v[226:227]
	v_mov_b64_e32 v[14:15], v[228:229]
	v_mov_b64_e32 v[16:17], v[230:231]
	s_cbranch_execnz .LBB0_167

; #define LAS __attribute__((address_space(3)))
; __global__ void __launch_bounds__(NTHR, 2) fwd_megakernel(Args a) {
;     extern __shared__ __attribute__((aligned(16))) unsigned char lds_raw[];
;     cg::grid_group grid = cg::this_grid();
;     LAS unsigned char* lds = (LAS unsigned char*)lds_raw;
;     const int tid = threadIdx.x, lane = tid & 63, wave = __builtin_amdgcn_readfirstlane(tid >> 6);
	.amdhsa_kernel _Z14fwd_megakernel4Args
		.amdhsa_group_segment_fixed_size 0
		.amdhsa_private_segment_fixed_size 0
		.amdhsa_kernarg_size 368
		.amdhsa_user_sgpr_count 2
		.amdhsa_user_sgpr_dispatch_ptr 0
		.amdhsa_user_sgpr_queue_ptr 0
		.amdhsa_user_sgpr_kernarg_segment_ptr 1
		.amdhsa_user_sgpr_dispatch_id 0
		.amdhsa_user_sgpr_kernarg_preload_length 0
		.amdhsa_user_sgpr_kernarg_preload_offset 0
		.amdhsa_user_sgpr_private_segment_size 0
		.amdhsa_uses_dynamic_stack 0
		.amdhsa_enable_private_segment 0
		.amdhsa_system_sgpr_workgroup_id_x 1
		.amdhsa_system_sgpr_workgroup_id_y 0
		.amdhsa_system_sgpr_workgroup_id_z 0
		.amdhsa_system_sgpr_workgroup_info 0
		.amdhsa_system_vgpr_workitem_id 2
		.amdhsa_next_free_vgpr 256
		.amdhsa_next_free_sgpr 102
		.amdhsa_accum_offset 256
		.amdhsa_reserve_vcc 1
		.amdhsa_float_round_mode_32 0
		.amdhsa_float_round_mode_16_64 0
		.amdhsa_float_denorm_mode_32 3
		.amdhsa_float_denorm_mode_16_64 3
		.amdhsa_dx10_clamp 1
		.amdhsa_ieee_mode 1
		.amdhsa_fp16_overflow 0
		.amdhsa_tg_split 0
		.amdhsa_exception_fp_ieee_invalid_op 0
		.amdhsa_exception_fp_denorm_src 0
		.amdhsa_exception_fp_ieee_div_zero 0
		.amdhsa_exception_fp_ieee_overflow 0
		.amdhsa_exception_fp_ieee_underflow 0
		.amdhsa_exception_fp_ieee_inexact 0
		.amdhsa_exception_int_div_zero 0
	.end_amdhsa_kernel

; __global__ void __launch_bounds__(NTHR, 2) fwd_megakernel(Args a) {
amdhsa.kernels:
  - .agpr_count:     0
    .args:
      - .offset:         0
        .size:           112
        .value_kind:     by_value
      - .offset:         112
        .size:           4
        .value_kind:     hidden_block_count_x
      - .offset:         116
        .size:           4
        .value_kind:     hidden_block_count_y
      - .offset:         120
        .size:           4
        .value_kind:     hidden_block_count_z
      - .offset:         124
        .size:           2
        .value_kind:     hidden_group_size_x
      - .offset:         126
        .size:           2
        .value_kind:     hidden_group_size_y
      - .offset:         128
        .size:           2
        .value_kind:     hidden_group_size_z
      - .offset:         130
        .size:           2
        .value_kind:     hidden_remainder_x
      - .offset:         132
        .size:           2
        .value_kind:     hidden_remainder_y
      - .offset:         134
        .size:           2
        .value_kind:     hidden_remainder_z
      - .offset:         152
        .size:           8
        .value_kind:     hidden_global_offset_x
      - .offset:         160
        .size:           8
        .value_kind:     hidden_global_offset_y
      - .offset:         168
        .size:           8
        .value_kind:     hidden_global_offset_z
      - .offset:         176
        .size:           2
        .value_kind:     hidden_grid_dims
      - .offset:         200
        .size:           8
        .value_kind:     hidden_multigrid_sync_arg
      - .offset:         232
        .size:           4
        .value_kind:     hidden_dynamic_lds_size
    .group_segment_fixed_size: 0
    .kernarg_segment_align: 8
    .kernarg_segment_size: 368
    .language:       OpenCL C
    .language_version:
      - 2
      - 0
    .max_flat_workgroup_size: 512
    .name:           _Z14fwd_megakernel4Args
    .private_segment_fixed_size: 0
    .sgpr_count:     108
    .sgpr_spill_count: 136
    .symbol:         _Z14fwd_megakernel4Args.kd
    .uniform_work_group_size: 1
    .uses_dynamic_stack: false
    .vgpr_count:     256
    .vgpr_spill_count: 0
    .wavefront_size: 64
